# C-attn plain tiles: next tile's LDS staging writes + global loads moved behind the QK MFMAs so the K fragment reads no longer queue behind the stage writes
# baseline (speedup 1.0000x reference)
; #define LAS __attribute__((address_space(3)))
; #define ATT_LOAD(kt) do { const long kb_ = (long)(kt) * 64; \
;         rk0 = *(const u32x4*)(a.k + (kb_ + kkey0) * a.k_rs + kpart0 * 8); \
;         if (DQK == 96 && tid < 256) rk1 = *(const u32x4*)(a.k + (kb_ + kkey1) * a.k_rs + kpart1 * 8); \
;         rv0 = *(const u32x2*)(a.v + (kb_ + 2 * vkp) * a.v_rs + vdg * 4); rv1 = *(const u32x2*)(a.v + (kb_ + 2 * vkp + 1) * a.v_rs + vdg * 4); } while (0)
; template <int DQK, int MODE>
; __device__ __forceinline__ void attn_unit(LAS unsigned char* lds, const AttnArgs& a, const unsigned char* lut) {
;     ...
;     for (int kt = kt_lo; kt <= kt_hi; ++kt) {
;         const int cur = (kt - kt_lo) & 1;
;         if (kt < kt_hi) ATT_STORE(cur ^ 1);
;         if (kt + 1 < kt_hi) ATT_LOAD(kt + 2);
;         const unsigned long long mwc0 = mwn0, mwc1 = mwn1;
;         if (MODE == 2 && kt < kt_hi) { mwn0 = a.mask[(long)qi * 128 + kt + 1]; mwn1 = a.mask[(long)(qi + 16) * 128 + kt + 1]; }
;         const LAS bf16_t* sK = (const LAS bf16_t*)(lds + cur * 24576); const LAS bf16_t* sVt = (const LAS bf16_t*)(lds + cur * 24576 + 14336);
;         const int key0 = kt * 64;
;         bool skip = key0 > wq_max;
;         if (MODE == 1) skip = skip || (key0 + 63 < wq_min - a.maxdist);
;         if (!skip) {
;             unsigned mlo[2] = {0u, 0u}, mhi[2] = {0u, 0u};
;             if (MODE == 0) {
;                 if (key0 + 63 <= wq_min) attn_tile<DQK, 0>(sK, sVt, sBias, qf, o, lsum, qi, key0, 0, mlo, mhi, nb, lr, lg);
;                 else attn_tile<DQK, 1>(sK, sVt, sBias, qf, o, lsum, qi, key0, 0, mlo, mhi, nb, lr, lg);
.LBB0_418:
	s_sub_i32 s0, s17, 63
	s_cmp_gt_i32 s0, s16
	s_cbranch_scc1 .Lmy_c_old418
	s_cmp_gt_i32 s17, s14
	s_cbranch_scc0 .Lmy_c_tile0

; #define LAS __attribute__((address_space(3)))
; #define ATT_LOAD(kt) do { const long kb_ = (long)(kt) * 64; \
;         rk0 = *(const u32x4*)(a.k + (kb_ + kkey0) * a.k_rs + kpart0 * 8); \
;         if (DQK == 96 && tid < 256) rk1 = *(const u32x4*)(a.k + (kb_ + kkey1) * a.k_rs + kpart1 * 8); \
;         rv0 = *(const u32x2*)(a.v + (kb_ + 2 * vkp) * a.v_rs + vdg * 4); rv1 = *(const u32x2*)(a.v + (kb_ + 2 * vkp + 1) * a.v_rs + vdg * 4); } while (0)
; template <int DQK, int VAR> ...
;     ...
;     for (int ch = 0; ch < 2; ++ch) {
;         bf16x8 kfr[2][DQK / 32];
; #pragma unroll
;         for (int c = 0; c < 2; ++c)
; #pragma unroll
;             for (int ks = 0; ks < DQK / 32; ++ks) kfr[c][ks] = *(const LAS bf16x8*)(sK + ((ch * 2 + c) * 16 + lr) * KP + ks * 32 + lg * 8);
;         __builtin_amdgcn_sched_barrier(0);
;         __builtin_amdgcn_s_setprio(1);
; #pragma unroll
;         for (int c = 0; c < 2; ++c) {
;             s[0][ch * 2 + c] = (f32x4){sinit, sinit, sinit, sinit}; s[1][ch * 2 + c] = s[0][ch * 2 + c];
; #pragma unroll
;             for (int ks = 0; ks < DQK / 32; ++ks) {
;                 s[0][ch * 2 + c] = __builtin_amdgcn_mfma_f32_16x16x32_bf16(kfr[c][ks], qf[0][ks], s[0][ch * 2 + c], 0, 0, 0);
;                 s[1][ch * 2 + c] = __builtin_amdgcn_mfma_f32_16x16x32_bf16(kfr[c][ks], qf[1][ks], s[1][ch * 2 + c], 0, 0, 0);
;             }
;         }
;         __builtin_amdgcn_s_setprio(0);
;         __builtin_amdgcn_sched_barrier(0);
;     }
; template <int DQK, int MODE>
; __device__ __forceinline__ void attn_unit(LAS unsigned char* lds, const AttnArgs& a, const unsigned char* lut) {
;     ...
;     ATT_LOAD(kt_lo);
;     ATT_STORE(0);
;     if (kt_lo < kt_hi) ATT_LOAD(kt_lo + 1);
;     unsigned long long mwn0 = 0ull, mwn1 = 0ull;
;     if (MODE == 2) { mwn0 = a.mask[(long)qi * 128 + kt_lo]; mwn1 = a.mask[(long)(qi + 16) * 128 + kt_lo]; }
;     __syncthreads();
;     for (int kt = kt_lo; kt <= kt_hi; ++kt) {
;         const int cur = (kt - kt_lo) & 1;
;         if (kt < kt_hi) ATT_STORE(cur ^ 1);
;         if (kt + 1 < kt_hi) ATT_LOAD(kt + 2);
.Lmy_c_tile0:
	s_mulk_i32 s20, 0x6000
	s_add_i32 s20, s20, 0
	v_add_u32_e32 v70, s20, v130
	v_add_u32_e32 v161, v70, v154
	ds_read_b128 v[90:93], v161
	ds_read_b128 v[86:89], v161 offset:64
	ds_read_b128 v[82:85], v161 offset:128
	ds_read_b128 v[78:81], v161 offset:3328
	ds_read_b128 v[74:77], v161 offset:3392
	ds_read_b128 v[70:73], v161 offset:3456
	v_add3_u32 v94, s20, v153, v155
	s_mov_b64 s[0:1], -1
	v_add_u32_e32 v157, 0x3800, v94
	s_setprio 1
	s_waitcnt lgkmcnt(5)
	v_mfma_f32_16x16x32_bf16 v[94:97], v[90:93], v[34:37], v[66:69]
	v_mfma_f32_16x16x32_bf16 v[98:101], v[90:93], v[46:49], v[66:69]
	s_waitcnt lgkmcnt(2)
	v_mfma_f32_16x16x32_bf16 v[102:105], v[78:81], v[34:37], v[66:69]
	v_mfma_f32_16x16x32_bf16 v[106:109], v[78:81], v[46:49], v[66:69]
	v_mfma_f32_16x16x32_bf16 v[94:97], v[86:89], v[38:41], v[94:97]
	v_mfma_f32_16x16x32_bf16 v[98:101], v[86:89], v[50:53], v[98:101]
	s_waitcnt lgkmcnt(1)
	v_mfma_f32_16x16x32_bf16 v[102:105], v[74:77], v[38:41], v[102:105]
	v_mfma_f32_16x16x32_bf16 v[106:109], v[74:77], v[50:53], v[106:109]
	v_mfma_f32_16x16x32_bf16 v[94:97], v[82:85], v[42:45], v[94:97]
	v_mfma_f32_16x16x32_bf16 v[98:101], v[82:85], v[54:57], v[98:101]
	s_waitcnt lgkmcnt(0)
	v_mfma_f32_16x16x32_bf16 v[102:105], v[70:73], v[42:45], v[102:105]
	v_mfma_f32_16x16x32_bf16 v[106:109], v[70:73], v[54:57], v[106:109]
	s_setprio 0
	ds_read_b128 v[110:113], v161 offset:6656
	ds_read_b128 v[114:117], v161 offset:6720
	ds_read_b128 v[118:121], v161 offset:6784
	ds_read_b128 v[122:125], v161 offset:9984
	ds_read_b128 v[162:165], v161 offset:10048
	ds_read_b128 v[166:169], v161 offset:10112
	s_setprio 1
	s_waitcnt lgkmcnt(5)
	v_mfma_f32_16x16x32_bf16 v[170:173], v[110:113], v[34:37], v[66:69]
	v_mfma_f32_16x16x32_bf16 v[110:113], v[110:113], v[46:49], v[66:69]
	s_waitcnt lgkmcnt(4)
	v_mfma_f32_16x16x32_bf16 v[170:173], v[114:117], v[38:41], v[170:173]
	v_mfma_f32_16x16x32_bf16 v[110:113], v[114:117], v[50:53], v[110:113]
	s_waitcnt lgkmcnt(3)
	v_mfma_f32_16x16x32_bf16 v[114:117], v[118:121], v[42:45], v[170:173]
	v_mfma_f32_16x16x32_bf16 v[110:113], v[118:121], v[54:57], v[110:113]
	s_waitcnt lgkmcnt(2)
	v_mfma_f32_16x16x32_bf16 v[118:121], v[122:125], v[34:37], v[66:69]
	v_mfma_f32_16x16x32_bf16 v[122:125], v[122:125], v[46:49], v[66:69]
	s_waitcnt lgkmcnt(1)
	v_mfma_f32_16x16x32_bf16 v[118:121], v[162:165], v[38:41], v[118:121]
	v_mfma_f32_16x16x32_bf16 v[122:125], v[162:165], v[50:53], v[122:125]
	s_waitcnt lgkmcnt(0)
	v_mfma_f32_16x16x32_bf16 v[118:121], v[166:169], v[42:45], v[118:121]
	v_mfma_f32_16x16x32_bf16 v[122:125], v[166:169], v[54:57], v[122:125]
	s_setprio 0
	s_setprio 0
	s_sub_i32 s19, 0x6000, s20
	v_add3_u32 v72, s19, v131, v146
	s_waitcnt vmcnt(2)
	ds_write_b128 v72, v[58:61]
	s_and_saveexec_b64 s[0:1], s[36:37]
	v_add3_u32 v72, s19, v147, v148
	ds_write_b128 v72, v[62:65]
	s_or_b64 exec, exec, s[0:1]
	s_waitcnt vmcnt(1)
	v_and_b32_e32 v72, 0xffff, v132
	v_add3_u32 v73, s19, v149, v150
	v_lshrrev_b32_e32 v74, 16, v132
	s_waitcnt vmcnt(0)
	v_lshl_or_b32 v72, v134, 16, v72
	v_and_or_b32 v74, v134, s69, v74
	v_add_u32_e32 v75, 0x3800, v73
	ds_write2_b32 v75, v72, v74 offset1:36
	v_and_b32_e32 v72, 0xffff, v133
	v_lshl_or_b32 v72, v135, 16, v72
	ds_write_b32 v73, v72 offset:14624
	v_lshrrev_b32_e32 v72, 16, v133
	v_and_or_b32 v72, v135, s69, v72
	v_add3_u32 v73, s19, v151, v150
	ds_write_b32 v73, v72 offset:14336
	s_add_i32 s19, s18, 1
	s_cmp_ge_i32 s19, s15
	s_cbranch_scc1 .Lmy_c_noload
	s_waitcnt vmcnt(2)
	v_lshl_add_u64 v[58:59], s[92:93], 0, v[140:141]
	global_load_dwordx4 v[58:61], v[58:59], off
	s_and_saveexec_b64 s[0:1], s[36:37]
	s_cbranch_execz .Lmy_c_423
	v_lshl_add_u64 v[62:63], s[92:93], 0, v[136:137]
	global_load_dwordx4 v[62:65], v[62:63], off

; template <int DQK, int VAR> ...
;     ...
; #pragma unroll
;     for (int kk = 0; kk < 2; ++kk)
; #pragma unroll
;         for (int dt = 0; dt < 4; ++dt) {
;             const LAS bf16_t* vp = sVt + (dt * 16 + lr) * VP + kk * 32 + lg * 4;
;             const u32x2 v0 = *(const LAS u32x2*)vp, v1 = *(const LAS u32x2*)(vp + 16);
;             vfr[kk][dt].x = v0.x; vfr[kk][dt].y = v0.y; vfr[kk][dt].z = v1.x; vfr[kk][dt].w = v1.y;
;         }
;     __builtin_amdgcn_sched_barrier(0);
; #pragma unroll
;     for (int qt = 0; qt < 2; ++qt) {
;         const int dq = qi + qt * 16 - key0 - lg * 4;
;         const LAS float* bp = sBias + (dq + 33);
;         float ps = 0.f;
; #pragma unroll
;         for (int c = 0; c < 4; ++c)
; #pragma unroll
;             for (int j = 0; j < 4; ++j) {
;                 float val = s[qt][c][j]; float pv;
;                 if (VAR == 0) pv = fexp2(val);
;                 else if (VAR == 1) { pv = fexp2(val); pv = (dq >= c * 16 + j) ? pv : 0.f; }
;                 else if (VAR == 2) { pv = fexp2(val + bp[63 - (c * 16 + j)]); }
;                 else if (VAR == 3) { pv = fexp2(val); pv = __uint_as_float(__float_as_uint(pv) & (unsigned)__builtin_amdgcn_sbfe((int)(c < 2 ? mlo[qt] : mhi[qt]), (c & 1) * 16 + j, 1)); }
;                 else { pv = fexp2(val + bp[63 - (c * 16 + j)]); pv = __uint_as_float(__float_as_uint(pv) & (unsigned)__builtin_amdgcn_sbfe((int)(c < 2 ? mlo[qt] : mhi[qt]), (c & 1) * 16 + j, 1)); }
;                 s[qt][c][j] = pv; ps += pv;
;             }
;         lsum[qt] += ps;
;     }
;     __builtin_amdgcn_s_setprio(1);
; #pragma unroll
;     for (int kk = 0; kk < 2; ++kk) {
;         bf16x8 pb[2];
; #pragma unroll
;         for (int qt = 0; qt < 2; ++qt) {
;             u32x4 pw; pw.x = pk2(s[qt][2 * kk][0], s[qt][2 * kk][1]); pw.y = pk2(s[qt][2 * kk][2], s[qt][2 * kk][3]); pw.z = pk2(s[qt][2 * kk + 1][0], s[qt][2 * kk + 1][1]); pw.w = pk2(s[qt][2 * kk + 1][2], s[qt][2 * kk + 1][3]);
;             pb[qt] = __builtin_bit_cast(bf16x8, pw);
;         }
; #pragma unroll
;         for (int dt = 0; dt < 4; ++dt) {
;             const bf16x8 vf = __builtin_bit_cast(bf16x8, vfr[kk][dt]);
;             o[0][dt] = __builtin_amdgcn_mfma_f32_16x16x32_bf16(vf, pb[0], o[0][dt], 0, 0, 0);
;             o[1][dt] = __builtin_amdgcn_mfma_f32_16x16x32_bf16(vf, pb[1], o[1][dt], 0, 0, 0);
;         }
;     }
.Lmy_c_noload:
	ds_read_b128 v[162:165], v157
	ds_read_b128 v[166:169], v157 offset:2304
	ds_read_b128 v[170:173], v157 offset:4608
	ds_read_b128 v[174:177], v157 offset:6912
	ds_read_b128 v[178:181], v157 offset:64
	ds_read_b128 v[182:185], v157 offset:2368
	ds_read_b128 v[186:189], v157 offset:4672
	ds_read_b128 v[218:221], v157 offset:6976
	v_exp_f32_e32 v191, v94
	v_exp_f32_e32 v190, v98
	v_exp_f32_e32 v201, v95
	v_exp_f32_e32 v200, v99
	v_exp_f32_e32 v215, v96
	v_exp_f32_e32 v214, v100
	v_exp_f32_e32 v223, v97
	v_exp_f32_e32 v222, v101
	v_exp_f32_e32 v225, v102
	v_exp_f32_e32 v224, v106
	v_pk_add_f32 v[94:95], v[190:191], 0 op_sel_hi:[1,0]
	v_exp_f32_e32 v231, v103
	v_exp_f32_e32 v230, v107
	v_pk_add_f32 v[94:95], v[200:201], v[94:95]
	v_exp_f32_e32 v233, v104
	v_exp_f32_e32 v232, v108
	v_pk_add_f32 v[94:95], v[214:215], v[94:95]
	v_exp_f32_e32 v235, v105
	v_exp_f32_e32 v234, v109
	v_pk_add_f32 v[94:95], v[222:223], v[94:95]
	v_exp_f32_e32 v237, v114
	v_exp_f32_e32 v236, v110
	v_pk_add_f32 v[94:95], v[94:95], v[224:225]
	v_exp_f32_e32 v239, v115
	v_pk_add_f32 v[94:95], v[230:231], v[94:95]
	v_exp_f32_e32 v238, v111
	v_exp_f32_e32 v241, v116
	v_pk_add_f32 v[94:95], v[232:233], v[94:95]
	v_exp_f32_e32 v240, v112
	v_exp_f32_e32 v243, v117
	v_pk_add_f32 v[94:95], v[234:235], v[94:95]
	v_exp_f32_e32 v242, v113
	v_exp_f32_e32 v245, v118
	v_pk_add_f32 v[94:95], v[94:95], v[236:237]
	v_exp_f32_e32 v244, v122
	v_exp_f32_e32 v247, v119
	v_exp_f32_e32 v246, v123
	v_pk_add_f32 v[94:95], v[238:239], v[94:95]
	v_exp_f32_e32 v249, v120
	v_exp_f32_e32 v248, v124
	v_pk_add_f32 v[94:95], v[240:241], v[94:95]
	v_exp_f32_e32 v203, v121
	v_pk_add_f32 v[94:95], v[242:243], v[94:95]
	v_exp_f32_e32 v202, v125
	v_pk_add_f32 v[94:95], v[94:95], v[244:245]
	s_nop 0
	v_pk_add_f32 v[94:95], v[246:247], v[94:95]
	s_nop 0
	v_pk_add_f32 v[94:95], v[248:249], v[94:95]
	s_nop 0
	v_pk_add_f32 v[144:145], v[202:203], v[94:95]
	s_setprio 1
	v_cvt_pk_bf16_f32 v94, v191, v201
	v_cvt_pk_bf16_f32 v95, v215, v223
	v_cvt_pk_bf16_f32 v96, v225, v231
	v_cvt_pk_bf16_f32 v97, v233, v235
	v_cvt_pk_bf16_f32 v98, v190, v200
	v_cvt_pk_bf16_f32 v99, v214, v222
	v_cvt_pk_bf16_f32 v100, v224, v230
	v_cvt_pk_bf16_f32 v101, v232, v234
	s_mov_b64 s[0:1], 0
	s_waitcnt lgkmcnt(7)
	v_mfma_f32_16x16x32_bf16 v[30:33], v[162:165], v[94:97], v[30:33]
	v_mfma_f32_16x16x32_bf16 v[14:17], v[162:165], v[98:101], v[14:17]
	s_waitcnt lgkmcnt(6)
	v_mfma_f32_16x16x32_bf16 v[26:29], v[166:169], v[94:97], v[26:29]
	v_mfma_f32_16x16x32_bf16 v[10:13], v[166:169], v[98:101], v[10:13]
	s_waitcnt lgkmcnt(5)
	v_mfma_f32_16x16x32_bf16 v[22:25], v[170:173], v[94:97], v[22:25]
	v_mfma_f32_16x16x32_bf16 v[6:9], v[170:173], v[98:101], v[6:9]
	v_cvt_pk_bf16_f32 v170, v237, v239
	v_cvt_pk_bf16_f32 v171, v241, v243
	v_cvt_pk_bf16_f32 v172, v245, v247
	s_waitcnt lgkmcnt(4)
	v_mfma_f32_16x16x32_bf16 v[18:21], v[174:177], v[94:97], v[18:21]
	v_cvt_pk_bf16_f32 v173, v249, v203
	v_mfma_f32_16x16x32_bf16 v[2:5], v[174:177], v[98:101], v[2:5]
	v_cvt_pk_bf16_f32 v174, v236, v238
	v_cvt_pk_bf16_f32 v175, v240, v242
	v_cvt_pk_bf16_f32 v176, v244, v246
	s_waitcnt lgkmcnt(3)
	v_mfma_f32_16x16x32_bf16 v[30:33], v[178:181], v[170:173], v[30:33]
	v_cvt_pk_bf16_f32 v177, v248, v202
	s_nop 0
	v_mfma_f32_16x16x32_bf16 v[14:17], v[178:181], v[174:177], v[14:17]
	s_waitcnt lgkmcnt(2)
	v_mfma_f32_16x16x32_bf16 v[26:29], v[182:185], v[170:173], v[26:29]
	v_mfma_f32_16x16x32_bf16 v[10:13], v[182:185], v[174:177], v[10:13]
	s_waitcnt lgkmcnt(1)
	v_mfma_f32_16x16x32_bf16 v[22:25], v[186:189], v[170:173], v[22:25]
	v_mfma_f32_16x16x32_bf16 v[6:9], v[186:189], v[174:177], v[6:9]
	s_waitcnt lgkmcnt(0)
	v_mfma_f32_16x16x32_bf16 v[18:21], v[218:221], v[170:173], v[18:21]
	v_mfma_f32_16x16x32_bf16 v[2:5], v[218:221], v[174:177], v[2:5]
	s_branch .LBB0_428
